# L0 NA attention window loop: 16 predicated serial bias ds_reads per tile replaced by one batch + cndmask
# baseline (speedup 1.0000x reference)
.LBB0_885:
	s_waitcnt vmcnt(0)
	ds_write_b128 v129, v[102:105] offset:4608
	ds_write_b128 v129, v[98:101] offset:5760
	ds_write_b128 v129, v[106:109] offset:6912
	ds_write_b128 v129, v[110:113] offset:8064
	ds_read_b128 v[50:53], v130 offset:4608
	ds_read_b128 v[98:101], v130 offset:4624
	ds_read_b128 v[102:105], v130 offset:4640
	ds_read_b128 v[106:109], v130 offset:4656
	s_waitcnt lgkmcnt(3)
	v_mfma_f32_32x32x16_bf16 v[50:65], v[50:53], v[82:85], 0
	s_add_i32 s42, s4, -5
	s_min_i32 s2, s42, s66
	s_add_i32 s2, s2, s78
	v_lshl_add_u32 v138, s2, 6, v131
	v_mad_i64_i32 v[110:111], s[48:49], v138, s44, v[126:127]
	s_waitcnt lgkmcnt(2)
	v_mfma_f32_32x32x16_bf16 v[50:65], v[98:101], v[86:89], v[50:65]
	global_load_dwordx4 v[98:101], v[110:111], off
	v_add_u32_e32 v137, s4, v133
	v_add_u32_e32 v114, -7, v137
	v_add_u32_e32 v135, s69, v132
	v_mov_b32_e32 v115, 0xff800000
	s_waitcnt lgkmcnt(1)
	v_mfma_f32_32x32x16_bf16 v[50:65], v[102:105], v[90:93], v[50:65]
	v_add_co_u32_e32 v102, vcc, 0xc000, v110
	s_nop 1
	v_addc_co_u32_e32 v103, vcc, 0, v111, vcc
	global_load_dwordx4 v[102:105], v[102:103], off
	s_waitcnt lgkmcnt(0)
	v_mfma_f32_32x32x16_bf16 v[50:65], v[106:109], v[94:97], v[50:65]
	v_add_co_u32_e32 v106, vcc, 0x18000, v110
	s_nop 1
	v_addc_co_u32_e32 v107, vcc, 0, v111, vcc
	v_add_co_u32_e32 v110, vcc, 0x24000, v110
	global_load_dwordx4 v[106:109], v[106:107], off
	s_nop 0
	v_addc_co_u32_e32 v111, vcc, 0, v111, vcc
	global_load_dwordx4 v[110:113], v[110:111], off
	v_cmp_gt_u32_e32 vcc, 8, v114
	ds_read_b32 v200, v135 offset:10400
	ds_read_b32 v201, v135 offset:10404
	ds_read_b32 v202, v135 offset:10408
	ds_read_b32 v203, v135 offset:10412
	ds_read_b32 v204, v135 offset:10432
	ds_read_b32 v205, v135 offset:10436
	ds_read_b32 v206, v135 offset:10440
	ds_read_b32 v207, v135 offset:10444
	ds_read_b32 v208, v135 offset:10464
	ds_read_b32 v209, v135 offset:10468
	ds_read_b32 v210, v135 offset:10472
	ds_read_b32 v211, v135 offset:10476
	ds_read_b32 v212, v135 offset:10496
	ds_read_b32 v213, v135 offset:10500
	ds_read_b32 v214, v135 offset:10504
	ds_read_b32 v215, v135 offset:10508
	s_waitcnt lgkmcnt(12)
	s_and_b64 s[48:49], vcc, s[6:7]
	v_add_f32_e32 v200, v34, v200
	v_cndmask_b32_e64 v115, v252, v200, s[48:49]
	s_and_b64 s[48:49], vcc, s[8:9]
	v_add_f32_e32 v201, v35, v201
	v_cndmask_b32_e64 v114, v252, v201, s[48:49]
	s_and_b64 s[48:49], vcc, s[10:11]
	v_add_f32_e32 v202, v36, v202
	v_cndmask_b32_e64 v35, v252, v202, s[48:49]
	s_and_b64 s[48:49], vcc, s[12:13]
	v_add_f32_e32 v203, v37, v203
	v_cndmask_b32_e64 v34, v252, v203, s[48:49]
	s_waitcnt lgkmcnt(8)
	s_and_b64 s[48:49], vcc, s[14:15]
	v_add_f32_e32 v204, v38, v204
	v_cndmask_b32_e64 v37, v252, v204, s[48:49]
	s_and_b64 s[48:49], vcc, s[16:17]
	v_add_f32_e32 v205, v39, v205
	v_cndmask_b32_e64 v36, v252, v205, s[48:49]
	s_and_b64 s[48:49], vcc, s[18:19]
	v_add_f32_e32 v206, v40, v206
	v_cndmask_b32_e64 v39, v252, v206, s[48:49]
	s_and_b64 s[48:49], vcc, s[20:21]
	v_add_f32_e32 v207, v41, v207
	v_cndmask_b32_e64 v38, v252, v207, s[48:49]
	s_waitcnt lgkmcnt(4)
	s_and_b64 s[48:49], vcc, s[22:23]
	v_add_f32_e32 v208, v42, v208
	v_cndmask_b32_e64 v116, v252, v208, s[48:49]
	s_and_b64 s[48:49], vcc, s[24:25]
	v_add_f32_e32 v209, v43, v209
	v_cndmask_b32_e64 v41, v252, v209, s[48:49]
	s_and_b64 s[48:49], vcc, s[26:27]
	v_add_f32_e32 v210, v44, v210
	v_cndmask_b32_e64 v118, v252, v210, s[48:49]
	s_and_b64 s[48:49], vcc, s[28:29]
	v_add_f32_e32 v211, v45, v211
	v_cndmask_b32_e64 v117, v252, v211, s[48:49]
	s_waitcnt lgkmcnt(0)
	s_and_b64 s[48:49], vcc, s[30:31]
	v_add_f32_e32 v212, v46, v212
	v_cndmask_b32_e64 v120, v252, v212, s[48:49]
	s_and_b64 s[48:49], vcc, s[34:35]
	v_add_f32_e32 v213, v47, v213
	v_cndmask_b32_e64 v119, v252, v213, s[48:49]
	s_and_b64 s[48:49], vcc, s[36:37]
	v_add_f32_e32 v214, v48, v214
	v_cndmask_b32_e64 v139, v252, v214, s[48:49]
	s_and_b64 s[48:49], vcc, s[38:39]
	v_add_f32_e32 v215, v49, v215
	v_cndmask_b32_e64 v121, v252, v215, s[48:49]
	v_max_f32_e32 v40, v114, v114
	v_max_f32_e32 v42, v115, v115
	v_max_f32_e32 v40, v42, v40
	v_max3_f32 v40, v40, v35, v34
	v_max3_f32 v40, v40, v37, v36
	v_max3_f32 v40, v40, v39, v38
	v_max3_f32 v40, v40, v116, v41
	v_max3_f32 v40, v40, v118, v117
	v_max3_f32 v40, v40, v120, v119
	v_max3_f32 v40, v40, v139, v121
	v_mov_b32_e32 v42, v40
	s_nop 1
	v_permlane32_swap_b32_e32 v40, v42
	v_max3_f32 v140, v123, v40, v42
	v_sub_f32_e32 v40, v115, v140
	v_exp_f32_e32 v40, v40
	v_sub_f32_e32 v42, v114, v140
	v_exp_f32_e32 v42, v42
	v_sub_f32_e32 v35, v35, v140
	v_exp_f32_e32 v35, v35
	v_sub_f32_e32 v34, v34, v140
	v_exp_f32_e32 v34, v34
	v_sub_f32_e32 v37, v37, v140
	v_add_f32_e32 v43, 0, v40
	v_exp_f32_e32 v37, v37
	v_sub_f32_e32 v36, v36, v140
	v_add_f32_e32 v43, v42, v43
	v_exp_f32_e32 v36, v36
	v_sub_f32_e32 v39, v39, v140
	v_add_f32_e32 v43, v35, v43
	v_exp_f32_e32 v39, v39
	v_sub_f32_e32 v38, v38, v140
	v_add_f32_e32 v43, v34, v43
	v_exp_f32_e32 v38, v38
	v_add_f32_e32 v43, v37, v43
	v_add_f32_e32 v43, v36, v43
	v_add_f32_e32 v43, v39, v43
	v_add_f32_e32 v46, v38, v43
	v_sub_f32_e32 v43, v116, v140
	v_exp_f32_e32 v43, v43
	v_sub_f32_e32 v41, v41, v140
	v_exp_f32_e32 v41, v41
	v_sub_f32_e32 v44, v118, v140
	v_exp_f32_e32 v44, v44
	v_sub_f32_e32 v45, v117, v140
	v_exp_f32_e32 v45, v45
	v_add_f32_e32 v46, v43, v46
	v_add_f32_e32 v46, v41, v46
	v_add_f32_e32 v46, v44, v46
	v_add_f32_e32 v114, v45, v46
	v_sub_f32_e32 v46, v120, v140
	v_exp_f32_e32 v46, v46
	v_sub_f32_e32 v47, v119, v140
	v_exp_f32_e32 v47, v47
	v_sub_f32_e32 v48, v139, v140
	v_exp_f32_e32 v48, v48
	v_sub_f32_e32 v49, v121, v140
	v_exp_f32_e32 v49, v49
	v_add_f32_e32 v114, v46, v114
	v_add_f32_e32 v114, v47, v114
	v_add_f32_e32 v114, v48, v114
	v_add_f32_e32 v139, v49, v114
	v_mov_b32_e32 v141, v139
	s_nop 1
	v_permlane32_swap_b32_e32 v139, v141
	v_cmp_gt_f32_e32 vcc, v140, v123
	s_cbranch_vccz .LBB0_919
	v_sub_f32_e32 v114, v123, v140
	v_exp_f32_e32 v114, v114
	s_nop 0
	v_mul_f32_e32 v136, v136, v114
	v_pk_mul_f32 v[32:33], v[32:33], v[114:115] op_sel_hi:[1,0]
	v_pk_mul_f32 v[30:31], v[30:31], v[114:115] op_sel_hi:[1,0]
	v_pk_mul_f32 v[28:29], v[28:29], v[114:115] op_sel_hi:[1,0]
	v_pk_mul_f32 v[26:27], v[26:27], v[114:115] op_sel_hi:[1,0]
	v_pk_mul_f32 v[24:25], v[24:25], v[114:115] op_sel_hi:[1,0]
	v_pk_mul_f32 v[22:23], v[22:23], v[114:115] op_sel_hi:[1,0]
	v_pk_mul_f32 v[20:21], v[20:21], v[114:115] op_sel_hi:[1,0]
	v_pk_mul_f32 v[18:19], v[18:19], v[114:115] op_sel_hi:[1,0]
	v_pk_mul_f32 v[16:17], v[16:17], v[114:115] op_sel_hi:[1,0]
	v_pk_mul_f32 v[14:15], v[14:15], v[114:115] op_sel_hi:[1,0]
	v_pk_mul_f32 v[12:13], v[12:13], v[114:115] op_sel_hi:[1,0]
	v_pk_mul_f32 v[10:11], v[10:11], v[114:115] op_sel_hi:[1,0]
	v_pk_mul_f32 v[8:9], v[8:9], v[114:115] op_sel_hi:[1,0]
	v_pk_mul_f32 v[6:7], v[6:7], v[114:115] op_sel_hi:[1,0]
	v_pk_mul_f32 v[4:5], v[4:5], v[114:115] op_sel_hi:[1,0]
	v_pk_mul_f32 v[2:3], v[2:3], v[114:115] op_sel_hi:[1,0]
.LBB0_919:
	v_cvt_pk_bf16_f32 v114, v40, v42
	v_cvt_pk_bf16_f32 v115, v35, v34
	v_cvt_pk_bf16_f32 v116, v37, v36
	v_cvt_pk_bf16_f32 v117, v39, v38
	v_cvt_pk_bf16_f32 v34, v43, v41
	v_cvt_pk_bf16_f32 v35, v44, v45
	v_cvt_pk_bf16_f32 v36, v46, v47
	v_cvt_pk_bf16_f32 v37, v48, v49
	ds_write_b128 v129, v[70:73]
	ds_write_b128 v129, v[66:69] offset:1152
	ds_write_b128 v129, v[74:77] offset:2304
	ds_write_b128 v129, v[78:81] offset:3456
	ds_read_b64_tr_b16 v[38:39], v134
	ds_read_b64_tr_b16 v[40:41], v134 offset:1152
	s_waitcnt lgkmcnt(0)
	v_mfma_f32_32x32x16_bf16 v[18:33], v[38:41], v[114:117], v[18:33]
	s_add_i32 s33, s4, -6
	ds_read_b64_tr_b16 v[42:43], v134 offset:2304
	ds_read_b64_tr_b16 v[44:45], v134 offset:3456
	ds_read_b64_tr_b16 v[48:49], v134 offset:1216
	ds_read_b64_tr_b16 v[46:47], v134 offset:64
	s_min_i32 s2, s33, s66
	s_add_i32 s2, s2, s78
	v_lshl_add_u32 v38, s2, 6, v131
	v_mad_i64_i32 v[74:75], s[48:49], v38, s44, v[124:125]
	s_waitcnt lgkmcnt(2)
	v_mfma_f32_32x32x16_bf16 v[18:33], v[42:45], v[34:37], v[18:33]
	v_add_co_u32_e32 v42, vcc, s46, v74
	ds_read_b64_tr_b16 v[40:41], v134 offset:3520
	ds_read_b64_tr_b16 v[38:39], v134 offset:2368
	v_addc_co_u32_e32 v43, vcc, 0, v75, vcc
	global_load_dwordx4 v[66:69], v[74:75], off
	global_load_dwordx4 v[70:73], v[42:43], off
	v_add_co_u32_e32 v42, vcc, s77, v74
	s_waitcnt lgkmcnt(2)
	v_mfma_f32_32x32x16_bf16 v[2:17], v[46:49], v[114:117], v[2:17]
	v_addc_co_u32_e32 v43, vcc, 0, v75, vcc
	v_add_co_u32_e32 v44, vcc, s45, v74
	s_add_i32 s2, s4, -4
	s_nop 0
	v_addc_co_u32_e32 v45, vcc, 0, v75, vcc
	global_load_dwordx4 v[114:117], v[42:43], off
	global_load_dwordx4 v[118:121], v[44:45], off
	s_waitcnt vmcnt(7)
	ds_write_b128 v129, v[98:101] offset:4608
	s_waitcnt vmcnt(6)
	ds_write_b128 v129, v[102:105] offset:5760
	s_waitcnt vmcnt(5)
	ds_write_b128 v129, v[106:109] offset:6912
	s_waitcnt vmcnt(4)
	ds_write_b128 v129, v[110:113] offset:8064
	s_waitcnt lgkmcnt(4)
	v_mfma_f32_32x32x16_bf16 v[2:17], v[38:41], v[34:37], v[2:17]
	ds_read_b128 v[34:37], v130 offset:4608
	ds_read_b128 v[74:77], v130 offset:4624
	s_min_i32 s43, s2, s66
	s_add_i32 s43, s43, s78
	v_lshl_add_u32 v123, s43, 6, v131
	v_mad_i64_i32 v[102:103], s[48:49], v123, s44, v[126:127]
	v_add_co_u32_e32 v78, vcc, s46, v102
	s_waitcnt lgkmcnt(1)
	v_mfma_f32_32x32x16_bf16 v[34:49], v[34:37], v[82:85], 0
	v_addc_co_u32_e32 v79, vcc, 0, v103, vcc
	v_add_co_u32_e32 v104, vcc, s77, v102
	s_cmp_lt_i32 s33, s5
	s_nop 0
	v_addc_co_u32_e32 v105, vcc, 0, v103, vcc
	s_waitcnt lgkmcnt(0)
	v_mfma_f32_32x32x16_bf16 v[34:49], v[74:77], v[86:89], v[34:49]
	ds_read_b128 v[74:77], v130 offset:4640
	ds_read_b128 v[98:101], v130 offset:4656
	s_waitcnt lgkmcnt(1)
	v_mfma_f32_32x32x16_bf16 v[34:49], v[74:77], v[90:93], v[34:49]
	global_load_dwordx4 v[74:77], v[102:103], off
	s_nop 0
	global_load_dwordx4 v[78:81], v[78:79], off
	v_add_co_u32_e32 v102, vcc, s45, v102
	s_nop 1
	v_addc_co_u32_e32 v103, vcc, 0, v103, vcc
	global_load_dwordx4 v[106:109], v[104:105], off
	global_load_dwordx4 v[110:113], v[102:103], off
	s_waitcnt lgkmcnt(0)
	v_mfma_f32_32x32x16_bf16 v[34:49], v[98:101], v[94:97], v[34:49]
	v_mov_b32_e32 v98, 0xff800000
	s_cselect_b64 vcc, -1, 0
	v_cndmask_b32_e32 v99, v98, v58, vcc
	v_cndmask_b32_e32 v58, v98, v55, vcc
	v_cndmask_b32_e32 v55, v98, v54, vcc
	v_cndmask_b32_e32 v54, v98, v51, vcc
	v_add_u32_e32 v51, -6, v137
	v_cndmask_b32_e32 v65, v98, v65, vcc
	v_cndmask_b32_e32 v64, v98, v64, vcc
	v_cndmask_b32_e32 v63, v98, v63, vcc
	v_cndmask_b32_e32 v62, v98, v62, vcc
	v_cndmask_b32_e32 v61, v98, v61, vcc
	v_cndmask_b32_e32 v60, v98, v60, vcc
	v_cndmask_b32_e32 v59, v98, v59, vcc
	v_cndmask_b32_e32 v100, v98, v57, vcc
	v_cndmask_b32_e32 v57, v98, v56, vcc
	v_cndmask_b32_e32 v56, v98, v53, vcc
	v_cndmask_b32_e32 v53, v98, v52, vcc
	v_cndmask_b32_e32 v50, v98, v50, vcc
	v_cmp_gt_u32_e32 vcc, 8, v51
	ds_read_b32 v200, v135 offset:10524
	ds_read_b32 v201, v135 offset:10528
	ds_read_b32 v202, v135 offset:10532
	ds_read_b32 v203, v135 offset:10536
	ds_read_b32 v204, v135 offset:10556
	ds_read_b32 v205, v135 offset:10560
	ds_read_b32 v206, v135 offset:10564
	ds_read_b32 v207, v135 offset:10568
	ds_read_b32 v208, v135 offset:10588
	ds_read_b32 v209, v135 offset:10592
	ds_read_b32 v210, v135 offset:10596
	ds_read_b32 v211, v135 offset:10600
	ds_read_b32 v212, v135 offset:10620
	ds_read_b32 v213, v135 offset:10624
	ds_read_b32 v214, v135 offset:10628
	ds_read_b32 v215, v135 offset:10632
	s_waitcnt lgkmcnt(12)
	s_and_b64 s[48:49], vcc, s[6:7]
	v_add_f32_e32 v200, v50, v200
	v_cndmask_b32_e64 v51, v252, v200, s[48:49]
	s_and_b64 s[48:49], vcc, s[8:9]
	v_add_f32_e32 v201, v54, v201
	v_cndmask_b32_e64 v52, v252, v201, s[48:49]
	s_and_b64 s[48:49], vcc, s[10:11]
	v_add_f32_e32 v202, v53, v202
	v_cndmask_b32_e64 v98, v252, v202, s[48:49]
	s_and_b64 s[48:49], vcc, s[12:13]
	v_add_f32_e32 v203, v56, v203
	v_cndmask_b32_e64 v54, v252, v203, s[48:49]
	s_waitcnt lgkmcnt(8)
	s_and_b64 s[48:49], vcc, s[14:15]
	v_add_f32_e32 v204, v55, v204
	v_cndmask_b32_e64 v53, v252, v204, s[48:49]
	s_and_b64 s[48:49], vcc, s[16:17]
	v_add_f32_e32 v205, v58, v205
	v_cndmask_b32_e64 v56, v252, v205, s[48:49]
	s_and_b64 s[48:49], vcc, s[18:19]
	v_add_f32_e32 v206, v57, v206
	v_cndmask_b32_e64 v55, v252, v206, s[48:49]
	s_and_b64 s[48:49], vcc, s[20:21]
	v_add_f32_e32 v207, v100, v207
	v_cndmask_b32_e64 v58, v252, v207, s[48:49]
	s_waitcnt lgkmcnt(4)
	s_and_b64 s[48:49], vcc, s[22:23]
	v_add_f32_e32 v208, v99, v208
	v_cndmask_b32_e64 v57, v252, v208, s[48:49]
	s_and_b64 s[48:49], vcc, s[24:25]
	v_add_f32_e32 v209, v59, v209
	v_cndmask_b32_e64 v100, v252, v209, s[48:49]
	s_and_b64 s[48:49], vcc, s[26:27]
	v_add_f32_e32 v210, v60, v210
	v_cndmask_b32_e64 v99, v252, v210, s[48:49]
	s_and_b64 s[48:49], vcc, s[28:29]
	v_add_f32_e32 v211, v61, v211
	v_cndmask_b32_e64 v102, v252, v211, s[48:49]
	s_waitcnt lgkmcnt(0)
	s_and_b64 s[48:49], vcc, s[30:31]
	v_add_f32_e32 v212, v62, v212
	v_cndmask_b32_e64 v101, v252, v212, s[48:49]
	s_and_b64 s[48:49], vcc, s[34:35]
	v_add_f32_e32 v213, v63, v213
	v_cndmask_b32_e64 v104, v252, v213, s[48:49]
	s_and_b64 s[48:49], vcc, s[36:37]
	v_add_f32_e32 v214, v64, v214
	v_cndmask_b32_e64 v103, v252, v214, s[48:49]
	s_and_b64 s[48:49], vcc, s[38:39]
	v_add_f32_e32 v215, v65, v215
	v_cndmask_b32_e64 v105, v252, v215, s[48:49]
	v_max_f32_e32 v59, v52, v52
	v_max_f32_e32 v60, v51, v51
	v_max_f32_e32 v59, v60, v59
	v_max3_f32 v59, v59, v98, v54
	v_max3_f32 v59, v59, v53, v56
	v_max3_f32 v59, v59, v55, v58
	v_max3_f32 v59, v59, v57, v100
	v_max3_f32 v59, v59, v99, v102
	v_max3_f32 v59, v59, v101, v104
	v_max3_f32 v59, v59, v103, v105
	v_mov_b32_e32 v60, v59
	s_nop 1
	v_permlane32_swap_b32_e32 v59, v60
	v_add_f32_e32 v50, v139, v141
	v_max3_f32 v139, v140, v59, v60
	v_sub_f32_e32 v51, v51, v139
	v_exp_f32_e32 v59, v51
	v_sub_f32_e32 v51, v52, v139
	v_exp_f32_e32 v60, v51
	v_sub_f32_e32 v51, v98, v139
	v_exp_f32_e32 v61, v51
	v_sub_f32_e32 v51, v54, v139
	v_exp_f32_e32 v54, v51
	v_sub_f32_e32 v52, v53, v139
	v_add_f32_e32 v51, 0, v59
	v_exp_f32_e32 v53, v52
	v_sub_f32_e32 v52, v56, v139
	v_add_f32_e32 v51, v60, v51
	v_exp_f32_e32 v56, v52
	v_sub_f32_e32 v52, v55, v139
	v_add_f32_e32 v51, v61, v51
	v_exp_f32_e32 v55, v52
	v_sub_f32_e32 v52, v58, v139
	v_add_f32_e32 v51, v54, v51
	v_exp_f32_e32 v58, v52
	v_sub_f32_e32 v52, v57, v139
	v_add_f32_e32 v51, v53, v51
	v_exp_f32_e32 v57, v52
	v_sub_f32_e32 v52, v100, v139
	v_add_f32_e32 v51, v56, v51
	v_exp_f32_e32 v62, v52
	v_sub_f32_e32 v52, v99, v139
	v_add_f32_e32 v51, v55, v51
	v_exp_f32_e32 v63, v52
	v_sub_f32_e32 v52, v102, v139
	v_add_f32_e32 v51, v58, v51
	v_exp_f32_e32 v64, v52
	v_sub_f32_e32 v52, v101, v139
	v_add_f32_e32 v51, v57, v51
	v_exp_f32_e32 v65, v52
	v_sub_f32_e32 v52, v104, v139
	v_add_f32_e32 v51, v62, v51
	v_exp_f32_e32 v98, v52
	v_sub_f32_e32 v52, v103, v139
	v_add_f32_e32 v51, v63, v51
	v_exp_f32_e32 v99, v52
	v_sub_f32_e32 v52, v105, v139
	v_add_f32_e32 v51, v64, v51
	v_exp_f32_e32 v100, v52
	v_add_f32_e32 v51, v65, v51
	v_add_f32_e32 v51, v98, v51
	v_add_f32_e32 v51, v99, v51
	v_add_f32_e32 v51, v100, v51
	v_mov_b32_e32 v52, v51
	v_add_f32_e32 v50, v50, v136
	s_nop 0
	v_permlane32_swap_b32_e32 v51, v52
	v_cmp_gt_f32_e32 vcc, v139, v140
	s_cbranch_vccz .LBB0_953
	v_sub_f32_e32 v101, v140, v139
	v_exp_f32_e32 v102, v101
	s_nop 0
	v_mul_f32_e32 v50, v50, v102
	v_pk_mul_f32 v[32:33], v[32:33], v[102:103] op_sel_hi:[1,0]
	v_pk_mul_f32 v[30:31], v[30:31], v[102:103] op_sel_hi:[1,0]
	v_pk_mul_f32 v[28:29], v[28:29], v[102:103] op_sel_hi:[1,0]
	v_pk_mul_f32 v[26:27], v[26:27], v[102:103] op_sel_hi:[1,0]
	v_pk_mul_f32 v[24:25], v[24:25], v[102:103] op_sel_hi:[1,0]
	v_pk_mul_f32 v[22:23], v[22:23], v[102:103] op_sel_hi:[1,0]
	v_pk_mul_f32 v[20:21], v[20:21], v[102:103] op_sel_hi:[1,0]
	v_pk_mul_f32 v[18:19], v[18:19], v[102:103] op_sel_hi:[1,0]
	v_pk_mul_f32 v[16:17], v[16:17], v[102:103] op_sel_hi:[1,0]
	v_pk_mul_f32 v[14:15], v[14:15], v[102:103] op_sel_hi:[1,0]
	v_pk_mul_f32 v[12:13], v[12:13], v[102:103] op_sel_hi:[1,0]
	v_pk_mul_f32 v[10:11], v[10:11], v[102:103] op_sel_hi:[1,0]
	v_pk_mul_f32 v[8:9], v[8:9], v[102:103] op_sel_hi:[1,0]
	v_pk_mul_f32 v[6:7], v[6:7], v[102:103] op_sel_hi:[1,0]
	v_pk_mul_f32 v[4:5], v[4:5], v[102:103] op_sel_hi:[1,0]
	v_pk_mul_f32 v[2:3], v[2:3], v[102:103] op_sel_hi:[1,0]
.LBB0_953:
	v_cvt_pk_bf16_f32 v102, v59, v60
	v_cvt_pk_bf16_f32 v103, v61, v54
	v_cvt_pk_bf16_f32 v104, v53, v56
	v_cvt_pk_bf16_f32 v105, v55, v58
	v_cvt_pk_bf16_f32 v54, v57, v62
	v_cvt_pk_bf16_f32 v55, v63, v64
	v_cvt_pk_bf16_f32 v56, v65, v98
	v_cvt_pk_bf16_f32 v57, v99, v100
	s_waitcnt vmcnt(7)
	ds_write_b128 v129, v[66:69]
	s_waitcnt vmcnt(6)
	ds_write_b128 v129, v[70:73] offset:1152
	s_waitcnt vmcnt(5)
	ds_write_b128 v129, v[114:117] offset:2304
	s_waitcnt vmcnt(4)
	ds_write_b128 v129, v[118:121] offset:3456
	ds_read_b64_tr_b16 v[58:59], v134
	ds_read_b64_tr_b16 v[60:61], v134 offset:1152
	s_waitcnt lgkmcnt(0)
	v_mfma_f32_32x32x16_bf16 v[18:33], v[58:61], v[102:105], v[18:33]
	v_mad_i64_i32 v[62:63], s[48:49], v138, s44, 0
	v_lshl_add_u64 v[114:115], v[124:125], 0, v[62:63]
	ds_read_b64_tr_b16 v[62:63], v134 offset:2304
	ds_read_b64_tr_b16 v[64:65], v134 offset:3456
	ds_read_b64_tr_b16 v[100:101], v134 offset:1216
	ds_read_b64_tr_b16 v[98:99], v134 offset:64
	v_add_co_u32_e32 v58, vcc, s46, v114
	v_add_f32_e32 v51, v51, v52
	s_nop 0
	v_addc_co_u32_e32 v59, vcc, 0, v115, vcc
	s_waitcnt lgkmcnt(2)
	v_mfma_f32_32x32x16_bf16 v[18:33], v[62:65], v[54:57], v[18:33]
	v_add_co_u32_e32 v62, vcc, s77, v114
	global_load_dwordx4 v[66:69], v[114:115], off
	global_load_dwordx4 v[70:73], v[58:59], off
	v_addc_co_u32_e32 v63, vcc, 0, v115, vcc
	v_add_co_u32_e32 v64, vcc, s45, v114
	ds_read_b64_tr_b16 v[60:61], v134 offset:3520
	ds_read_b64_tr_b16 v[58:59], v134 offset:2368
	v_addc_co_u32_e32 v65, vcc, 0, v115, vcc
	s_waitcnt lgkmcnt(2)
	v_mfma_f32_32x32x16_bf16 v[2:17], v[98:101], v[102:105], v[2:17]
	global_load_dwordx4 v[98:101], v[62:63], off
	global_load_dwordx4 v[102:105], v[64:65], off
	v_add_f32_e32 v136, v51, v50
	s_cmp_ge_i32 s42, s5
	s_mov_b64 s[64:65], -1
	s_waitcnt lgkmcnt(0)
	v_mfma_f32_32x32x16_bf16 v[2:17], v[58:61], v[54:57], v[2:17]
	s_cbranch_scc1 .LBB0_884
	s_waitcnt vmcnt(7)
	ds_write_b128 v129, v[74:77] offset:4608
	s_waitcnt vmcnt(6)
	ds_write_b128 v129, v[78:81] offset:5760
	s_waitcnt vmcnt(5)
	ds_write_b128 v129, v[106:109] offset:6912
	s_waitcnt vmcnt(4)
	ds_write_b128 v129, v[110:113] offset:8064
	ds_read_b128 v[50:53], v130 offset:4608
	ds_read_b128 v[74:77], v130 offset:4624
	ds_read_b128 v[78:81], v130 offset:4640
	ds_read_b128 v[106:109], v130 offset:4656
	s_waitcnt lgkmcnt(3)
	v_mfma_f32_32x32x16_bf16 v[50:65], v[50:53], v[82:85], 0
	s_add_i32 s43, s4, -3
	s_min_i32 s33, s43, s66
	s_add_i32 s33, s33, s78
	v_lshl_add_u32 v115, s33, 6, v131
	v_mad_i64_i32 v[110:111], s[48:49], v115, s44, v[126:127]
	s_waitcnt lgkmcnt(2)
	v_mfma_f32_32x32x16_bf16 v[50:65], v[74:77], v[86:89], v[50:65]
	global_load_dwordx4 v[74:77], v[110:111], off
	v_add_u32_e32 v114, -5, v137
	v_mov_b32_e32 v116, 0xff800000
	s_waitcnt lgkmcnt(1)
	v_mfma_f32_32x32x16_bf16 v[50:65], v[78:81], v[90:93], v[50:65]
	v_add_co_u32_e32 v78, vcc, 0xc000, v110
	s_nop 1
	v_addc_co_u32_e32 v79, vcc, 0, v111, vcc
	global_load_dwordx4 v[78:81], v[78:79], off
	s_waitcnt lgkmcnt(0)
	v_mfma_f32_32x32x16_bf16 v[50:65], v[106:109], v[94:97], v[50:65]
	v_add_co_u32_e32 v106, vcc, 0x18000, v110
	s_nop 1
	v_addc_co_u32_e32 v107, vcc, 0, v111, vcc
	v_add_co_u32_e32 v110, vcc, 0x24000, v110
	global_load_dwordx4 v[106:109], v[106:107], off
	s_nop 0
	v_addc_co_u32_e32 v111, vcc, 0, v111, vcc
	global_load_dwordx4 v[110:113], v[110:111], off
	v_cmp_gt_u32_e32 vcc, 8, v114
	ds_read_b32 v200, v135 offset:10648
	ds_read_b32 v201, v135 offset:10652
	ds_read_b32 v202, v135 offset:10656
	ds_read_b32 v203, v135 offset:10660
	ds_read_b32 v204, v135 offset:10680
	ds_read_b32 v205, v135 offset:10684
	ds_read_b32 v206, v135 offset:10688
	ds_read_b32 v207, v135 offset:10692
	ds_read_b32 v208, v135 offset:10712
	ds_read_b32 v209, v135 offset:10716
	ds_read_b32 v210, v135 offset:10720
	ds_read_b32 v211, v135 offset:10724
	ds_read_b32 v212, v135 offset:10744
	ds_read_b32 v213, v135 offset:10748
	ds_read_b32 v214, v135 offset:10752
	ds_read_b32 v215, v135 offset:10756
	s_waitcnt lgkmcnt(12)
	s_and_b64 s[48:49], vcc, s[6:7]
	v_add_f32_e32 v200, v34, v200
	v_cndmask_b32_e64 v116, v252, v200, s[48:49]
	s_and_b64 s[48:49], vcc, s[8:9]
	v_add_f32_e32 v201, v35, v201
	v_cndmask_b32_e64 v114, v252, v201, s[48:49]
	s_and_b64 s[48:49], vcc, s[10:11]
	v_add_f32_e32 v202, v36, v202
	v_cndmask_b32_e64 v35, v252, v202, s[48:49]
	s_and_b64 s[48:49], vcc, s[12:13]
	v_add_f32_e32 v203, v37, v203
	v_cndmask_b32_e64 v34, v252, v203, s[48:49]
	s_waitcnt lgkmcnt(8)
	s_and_b64 s[48:49], vcc, s[14:15]
	v_add_f32_e32 v204, v38, v204
	v_cndmask_b32_e64 v37, v252, v204, s[48:49]
	s_and_b64 s[48:49], vcc, s[16:17]
	v_add_f32_e32 v205, v39, v205
	v_cndmask_b32_e64 v36, v252, v205, s[48:49]
	s_and_b64 s[48:49], vcc, s[18:19]
	v_add_f32_e32 v206, v40, v206
	v_cndmask_b32_e64 v39, v252, v206, s[48:49]
	s_and_b64 s[48:49], vcc, s[20:21]
	v_add_f32_e32 v207, v41, v207
	v_cndmask_b32_e64 v38, v252, v207, s[48:49]
	s_waitcnt lgkmcnt(4)
	s_and_b64 s[48:49], vcc, s[22:23]
	v_add_f32_e32 v208, v42, v208
	v_cndmask_b32_e64 v119, v252, v208, s[48:49]
	s_and_b64 s[48:49], vcc, s[24:25]
	v_add_f32_e32 v209, v43, v209
	v_cndmask_b32_e64 v118, v252, v209, s[48:49]
	s_and_b64 s[48:49], vcc, s[26:27]
	v_add_f32_e32 v210, v44, v210
	v_cndmask_b32_e64 v121, v252, v210, s[48:49]
	s_and_b64 s[48:49], vcc, s[28:29]
	v_add_f32_e32 v211, v45, v211
	v_cndmask_b32_e64 v120, v252, v211, s[48:49]
	s_waitcnt lgkmcnt(0)
	s_and_b64 s[48:49], vcc, s[30:31]
	v_add_f32_e32 v212, v46, v212
	v_cndmask_b32_e64 v140, v252, v212, s[48:49]
	s_and_b64 s[48:49], vcc, s[34:35]
	v_add_f32_e32 v213, v47, v213
	v_cndmask_b32_e64 v138, v252, v213, s[48:49]
	s_and_b64 s[48:49], vcc, s[36:37]
	v_add_f32_e32 v214, v48, v214
	v_cndmask_b32_e64 v142, v252, v214, s[48:49]
	s_and_b64 s[48:49], vcc, s[38:39]
	v_add_f32_e32 v215, v49, v215
	v_cndmask_b32_e64 v141, v252, v215, s[48:49]
	v_max_f32_e32 v40, v114, v114
	v_max_f32_e32 v41, v116, v116
	v_max_f32_e32 v40, v41, v40
	v_max3_f32 v40, v40, v35, v34
	v_max3_f32 v40, v40, v37, v36
	v_max3_f32 v40, v40, v39, v38
	v_max3_f32 v40, v40, v119, v118
	v_max3_f32 v40, v40, v121, v120
	v_max3_f32 v40, v40, v140, v138
	v_max3_f32 v40, v40, v142, v141
	v_mov_b32_e32 v41, v40
	s_nop 1
	v_permlane32_swap_b32_e32 v40, v41
	v_max3_f32 v117, v139, v40, v41
	v_sub_f32_e32 v40, v116, v117
	v_exp_f32_e32 v40, v40
	v_sub_f32_e32 v41, v114, v117
	v_exp_f32_e32 v41, v41
	v_sub_f32_e32 v35, v35, v117
	v_exp_f32_e32 v35, v35
	v_sub_f32_e32 v34, v34, v117
	v_exp_f32_e32 v34, v34
	v_sub_f32_e32 v37, v37, v117
	v_add_f32_e32 v42, 0, v40
	v_exp_f32_e32 v37, v37
	v_sub_f32_e32 v36, v36, v117
	v_add_f32_e32 v42, v41, v42
	v_exp_f32_e32 v36, v36
	v_sub_f32_e32 v39, v39, v117
	v_add_f32_e32 v42, v35, v42
	v_exp_f32_e32 v39, v39
	v_sub_f32_e32 v38, v38, v117
	v_add_f32_e32 v42, v34, v42
	v_exp_f32_e32 v38, v38
	v_add_f32_e32 v42, v37, v42
	v_add_f32_e32 v42, v36, v42
	v_add_f32_e32 v42, v39, v42
	v_add_f32_e32 v46, v38, v42
	v_sub_f32_e32 v42, v119, v117
	v_exp_f32_e32 v42, v42
	v_sub_f32_e32 v43, v118, v117
	v_exp_f32_e32 v43, v43
	v_sub_f32_e32 v44, v121, v117
	v_exp_f32_e32 v44, v44
	v_sub_f32_e32 v45, v120, v117
	v_exp_f32_e32 v45, v45
	v_add_f32_e32 v46, v42, v46
	v_add_f32_e32 v46, v43, v46
	v_add_f32_e32 v46, v44, v46
	v_add_f32_e32 v114, v45, v46
	v_sub_f32_e32 v46, v140, v117
	v_exp_f32_e32 v46, v46
	v_sub_f32_e32 v47, v138, v117
	v_exp_f32_e32 v47, v47
	v_sub_f32_e32 v48, v142, v117
	v_exp_f32_e32 v48, v48
	v_sub_f32_e32 v49, v141, v117
	v_exp_f32_e32 v49, v49
	v_add_f32_e32 v114, v46, v114
	v_add_f32_e32 v114, v47, v114
	v_add_f32_e32 v114, v48, v114
	v_add_f32_e32 v116, v49, v114
	v_mov_b32_e32 v118, v116
	s_nop 1
	v_permlane32_swap_b32_e32 v116, v118
	v_cmp_gt_f32_e32 vcc, v117, v139
	s_cbranch_vccz .LBB0_988
	v_sub_f32_e32 v114, v139, v117
	v_exp_f32_e32 v114, v114
	s_nop 0
	v_mul_f32_e32 v136, v136, v114
	v_pk_mul_f32 v[32:33], v[32:33], v[114:115] op_sel_hi:[1,0]
	v_pk_mul_f32 v[30:31], v[30:31], v[114:115] op_sel_hi:[1,0]
	v_pk_mul_f32 v[28:29], v[28:29], v[114:115] op_sel_hi:[1,0]
	v_pk_mul_f32 v[26:27], v[26:27], v[114:115] op_sel_hi:[1,0]
	v_pk_mul_f32 v[24:25], v[24:25], v[114:115] op_sel_hi:[1,0]
	v_pk_mul_f32 v[22:23], v[22:23], v[114:115] op_sel_hi:[1,0]
	v_pk_mul_f32 v[20:21], v[20:21], v[114:115] op_sel_hi:[1,0]
	v_pk_mul_f32 v[18:19], v[18:19], v[114:115] op_sel_hi:[1,0]
	v_pk_mul_f32 v[16:17], v[16:17], v[114:115] op_sel_hi:[1,0]
	v_pk_mul_f32 v[14:15], v[14:15], v[114:115] op_sel_hi:[1,0]
	v_pk_mul_f32 v[12:13], v[12:13], v[114:115] op_sel_hi:[1,0]
	v_pk_mul_f32 v[10:11], v[10:11], v[114:115] op_sel_hi:[1,0]
	v_pk_mul_f32 v[8:9], v[8:9], v[114:115] op_sel_hi:[1,0]
	v_pk_mul_f32 v[6:7], v[6:7], v[114:115] op_sel_hi:[1,0]
	v_pk_mul_f32 v[4:5], v[4:5], v[114:115] op_sel_hi:[1,0]
	v_pk_mul_f32 v[2:3], v[2:3], v[114:115] op_sel_hi:[1,0]
.LBB0_988:
	v_cvt_pk_bf16_f32 v138, v40, v41
	v_cvt_pk_bf16_f32 v139, v35, v34
	v_cvt_pk_bf16_f32 v140, v37, v36
	v_cvt_pk_bf16_f32 v141, v39, v38
	v_cvt_pk_bf16_f32 v34, v42, v43
	v_cvt_pk_bf16_f32 v35, v44, v45
	v_cvt_pk_bf16_f32 v36, v46, v47
	v_cvt_pk_bf16_f32 v37, v48, v49
	s_waitcnt vmcnt(7)
	ds_write_b128 v129, v[66:69]
	s_waitcnt vmcnt(6)
	ds_write_b128 v129, v[70:73] offset:1152
	s_waitcnt vmcnt(5)
	ds_write_b128 v129, v[98:101] offset:2304
	s_waitcnt vmcnt(4)
	ds_write_b128 v129, v[102:105] offset:3456
	ds_read_b64_tr_b16 v[38:39], v134
	ds_read_b64_tr_b16 v[40:41], v134 offset:1152
	ds_read_b64_tr_b16 v[44:45], v134 offset:1216
	ds_read_b64_tr_b16 v[42:43], v134 offset:64
	s_waitcnt lgkmcnt(2)
	v_mfma_f32_32x32x16_bf16 v[18:33], v[38:41], v[138:141], v[18:33]
	ds_read_b64_tr_b16 v[38:39], v134 offset:2304
	ds_read_b64_tr_b16 v[40:41], v134 offset:3456
	v_mad_i64_i32 v[46:47], s[48:49], v123, s44, 0
	v_lshl_add_u64 v[98:99], v[124:125], 0, v[46:47]
	ds_read_b64_tr_b16 v[48:49], v134 offset:3520
	ds_read_b64_tr_b16 v[46:47], v134 offset:2368
	s_add_i32 s42, s4, -2
	s_min_i32 s33, s42, s66
	s_waitcnt lgkmcnt(2)
	v_mfma_f32_32x32x16_bf16 v[18:33], v[38:41], v[34:37], v[18:33]
	v_add_co_u32_e32 v38, vcc, s46, v98
	s_add_i32 s33, s33, s78
	s_nop 0
	v_addc_co_u32_e32 v39, vcc, 0, v99, vcc
	global_load_dwordx4 v[66:69], v[98:99], off
	global_load_dwordx4 v[70:73], v[38:39], off
	v_add_co_u32_e32 v38, vcc, s77, v98
	v_mfma_f32_32x32x16_bf16 v[2:17], v[42:45], v[138:141], v[2:17]
	s_nop 0
	v_addc_co_u32_e32 v39, vcc, 0, v99, vcc
	v_add_co_u32_e32 v40, vcc, s45, v98
	v_lshl_add_u32 v114, s33, 6, v131
	s_nop 0
	v_addc_co_u32_e32 v41, vcc, 0, v99, vcc
	global_load_dwordx4 v[98:101], v[38:39], off
	global_load_dwordx4 v[102:105], v[40:41], off
	s_waitcnt vmcnt(7)
	ds_write_b128 v129, v[74:77] offset:4608
	s_waitcnt vmcnt(6)
	ds_write_b128 v129, v[78:81] offset:5760
	s_waitcnt vmcnt(5)
	ds_write_b128 v129, v[106:109] offset:6912
	s_waitcnt vmcnt(4)
	ds_write_b128 v129, v[110:113] offset:8064
	s_waitcnt lgkmcnt(4)
	v_mfma_f32_32x32x16_bf16 v[2:17], v[46:49], v[34:37], v[2:17]
	ds_read_b128 v[34:37], v130 offset:4608
	ds_read_b128 v[74:77], v130 offset:4624
	v_mad_i64_i32 v[106:107], s[48:49], v114, s44, v[126:127]
	v_add_co_u32_e32 v78, vcc, s46, v106
	s_cmp_lt_i32 s2, s5
	s_nop 0
	v_addc_co_u32_e32 v79, vcc, 0, v107, vcc
	s_waitcnt lgkmcnt(1)
	v_mfma_f32_32x32x16_bf16 v[34:49], v[34:37], v[82:85], 0
	v_add_co_u32_e32 v108, vcc, s77, v106
	v_mov_b32_e32 v119, 0xff800000
	s_nop 0
	v_addc_co_u32_e32 v109, vcc, 0, v107, vcc
	v_add_co_u32_e32 v110, vcc, s45, v106
	s_waitcnt lgkmcnt(0)
	v_mfma_f32_32x32x16_bf16 v[34:49], v[74:77], v[86:89], v[34:49]
	ds_read_b128 v[74:77], v130 offset:4640
	ds_read_b128 v[138:141], v130 offset:4656
	v_addc_co_u32_e32 v111, vcc, 0, v107, vcc
	s_cselect_b64 vcc, -1, 0
	s_nop 0
	v_cndmask_b32_e32 v120, v119, v58, vcc
	v_cndmask_b32_e32 v58, v119, v55, vcc
	s_waitcnt lgkmcnt(1)
	v_mfma_f32_32x32x16_bf16 v[34:49], v[74:77], v[90:93], v[34:49]
	global_load_dwordx4 v[74:77], v[106:107], off
	s_nop 0
	global_load_dwordx4 v[78:81], v[78:79], off
	s_nop 0
	global_load_dwordx4 v[106:109], v[108:109], off
	s_nop 0
	global_load_dwordx4 v[110:113], v[110:111], off
	v_cndmask_b32_e32 v55, v119, v54, vcc
	v_cndmask_b32_e32 v54, v119, v51, vcc
	v_add_u32_e32 v51, -4, v137
	v_cndmask_b32_e32 v65, v119, v65, vcc
	v_cndmask_b32_e32 v64, v119, v64, vcc
	s_waitcnt lgkmcnt(0)
	v_mfma_f32_32x32x16_bf16 v[34:49], v[138:141], v[94:97], v[34:49]
	v_cndmask_b32_e32 v63, v119, v63, vcc
	v_cndmask_b32_e32 v62, v119, v62, vcc
	v_cndmask_b32_e32 v61, v119, v61, vcc
	v_cndmask_b32_e32 v60, v119, v60, vcc
	v_cndmask_b32_e32 v59, v119, v59, vcc
	v_cndmask_b32_e32 v121, v119, v57, vcc
	v_cndmask_b32_e32 v57, v119, v56, vcc
	v_cndmask_b32_e32 v56, v119, v53, vcc
	v_cndmask_b32_e32 v53, v119, v52, vcc
	v_cndmask_b32_e32 v50, v119, v50, vcc
	v_cmp_gt_u32_e32 vcc, 8, v51
	ds_read_b32 v200, v135 offset:10772
	ds_read_b32 v201, v135 offset:10776
	ds_read_b32 v202, v135 offset:10780
	ds_read_b32 v203, v135 offset:10784
	ds_read_b32 v204, v135 offset:10804
	ds_read_b32 v205, v135 offset:10808
	ds_read_b32 v206, v135 offset:10812
	ds_read_b32 v207, v135 offset:10816
	ds_read_b32 v208, v135 offset:10836
	ds_read_b32 v209, v135 offset:10840
	ds_read_b32 v210, v135 offset:10844
	ds_read_b32 v211, v135 offset:10848
	ds_read_b32 v212, v135 offset:10868
	ds_read_b32 v213, v135 offset:10872
	ds_read_b32 v214, v135 offset:10876
	ds_read_b32 v215, v135 offset:10880
	s_waitcnt lgkmcnt(12)
	s_and_b64 s[48:49], vcc, s[6:7]
	v_add_f32_e32 v200, v50, v200
	v_cndmask_b32_e64 v51, v252, v200, s[48:49]
	s_and_b64 s[48:49], vcc, s[8:9]
	v_add_f32_e32 v201, v54, v201
	v_cndmask_b32_e64 v52, v252, v201, s[48:49]
	s_and_b64 s[48:49], vcc, s[10:11]
	v_add_f32_e32 v202, v53, v202
	v_cndmask_b32_e64 v119, v252, v202, s[48:49]
	s_and_b64 s[48:49], vcc, s[12:13]
	v_add_f32_e32 v203, v56, v203
	v_cndmask_b32_e64 v54, v252, v203, s[48:49]
	s_waitcnt lgkmcnt(8)
	s_and_b64 s[48:49], vcc, s[14:15]
	v_add_f32_e32 v204, v55, v204
	v_cndmask_b32_e64 v53, v252, v204, s[48:49]
	s_and_b64 s[48:49], vcc, s[16:17]
	v_add_f32_e32 v205, v58, v205
	v_cndmask_b32_e64 v56, v252, v205, s[48:49]
	s_and_b64 s[48:49], vcc, s[18:19]
	v_add_f32_e32 v206, v57, v206
	v_cndmask_b32_e64 v55, v252, v206, s[48:49]
	s_and_b64 s[48:49], vcc, s[20:21]
	v_add_f32_e32 v207, v121, v207
	v_cndmask_b32_e64 v58, v252, v207, s[48:49]
	s_waitcnt lgkmcnt(4)
	s_and_b64 s[48:49], vcc, s[22:23]
	v_add_f32_e32 v208, v120, v208
	v_cndmask_b32_e64 v57, v252, v208, s[48:49]
	s_and_b64 s[48:49], vcc, s[24:25]
	v_add_f32_e32 v209, v59, v209
	v_cndmask_b32_e64 v121, v252, v209, s[48:49]
	s_and_b64 s[48:49], vcc, s[26:27]
	v_add_f32_e32 v210, v60, v210
	v_cndmask_b32_e64 v120, v252, v210, s[48:49]
	s_and_b64 s[48:49], vcc, s[28:29]
	v_add_f32_e32 v211, v61, v211
	v_cndmask_b32_e64 v138, v252, v211, s[48:49]
	s_waitcnt lgkmcnt(0)
	s_and_b64 s[48:49], vcc, s[30:31]
	v_add_f32_e32 v212, v62, v212
	v_cndmask_b32_e64 v123, v252, v212, s[48:49]
	s_and_b64 s[48:49], vcc, s[34:35]
	v_add_f32_e32 v213, v63, v213
	v_cndmask_b32_e64 v140, v252, v213, s[48:49]
	s_and_b64 s[48:49], vcc, s[36:37]
	v_add_f32_e32 v214, v64, v214
	v_cndmask_b32_e64 v139, v252, v214, s[48:49]
	s_and_b64 s[48:49], vcc, s[38:39]
	v_add_f32_e32 v215, v65, v215
	v_cndmask_b32_e64 v141, v252, v215, s[48:49]
	v_max_f32_e32 v59, v52, v52
	v_max_f32_e32 v60, v51, v51
	v_max_f32_e32 v59, v60, v59
	v_max3_f32 v59, v59, v119, v54
	v_max3_f32 v59, v59, v53, v56
	v_max3_f32 v59, v59, v55, v58
	v_max3_f32 v59, v59, v57, v121
	v_max3_f32 v59, v59, v120, v138
	v_max3_f32 v59, v59, v123, v140
	v_max3_f32 v59, v59, v139, v141
	v_mov_b32_e32 v60, v59
	s_nop 1
	v_permlane32_swap_b32_e32 v59, v60
	v_add_f32_e32 v50, v116, v118
	v_max3_f32 v116, v117, v59, v60
	v_sub_f32_e32 v51, v51, v116
	v_exp_f32_e32 v59, v51
	v_sub_f32_e32 v51, v52, v116
	v_exp_f32_e32 v60, v51
	v_sub_f32_e32 v51, v119, v116
	v_exp_f32_e32 v61, v51
	v_sub_f32_e32 v51, v54, v116
	v_exp_f32_e32 v54, v51
	v_sub_f32_e32 v52, v53, v116
	v_add_f32_e32 v51, 0, v59
	v_exp_f32_e32 v53, v52
	v_sub_f32_e32 v52, v56, v116
	v_add_f32_e32 v51, v60, v51
	v_exp_f32_e32 v56, v52
	v_sub_f32_e32 v52, v55, v116
	v_add_f32_e32 v51, v61, v51
	v_exp_f32_e32 v55, v52
	v_sub_f32_e32 v52, v58, v116
	v_add_f32_e32 v51, v54, v51
	v_exp_f32_e32 v58, v52
	v_sub_f32_e32 v52, v57, v116
	v_add_f32_e32 v51, v53, v51
	v_exp_f32_e32 v57, v52
	v_sub_f32_e32 v52, v121, v116
	v_add_f32_e32 v51, v56, v51
	v_exp_f32_e32 v62, v52
	v_sub_f32_e32 v52, v120, v116
	v_add_f32_e32 v51, v55, v51
	v_exp_f32_e32 v63, v52
	v_sub_f32_e32 v52, v138, v116
	v_add_f32_e32 v51, v58, v51
	v_exp_f32_e32 v64, v52
	v_sub_f32_e32 v52, v123, v116
	v_add_f32_e32 v51, v57, v51
	v_exp_f32_e32 v65, v52
	v_sub_f32_e32 v52, v140, v116
	v_add_f32_e32 v51, v62, v51
	v_exp_f32_e32 v118, v52
	v_sub_f32_e32 v52, v139, v116
	v_add_f32_e32 v51, v63, v51
	v_exp_f32_e32 v119, v52
	v_sub_f32_e32 v52, v141, v116
	v_add_f32_e32 v51, v64, v51
	v_exp_f32_e32 v120, v52
	v_add_f32_e32 v51, v65, v51
	v_add_f32_e32 v51, v118, v51
	v_add_f32_e32 v51, v119, v51
	v_add_f32_e32 v51, v120, v51
	v_mov_b32_e32 v52, v51
	v_add_f32_e32 v50, v50, v136
	s_nop 0
	v_permlane32_swap_b32_e32 v51, v52
	v_cmp_gt_f32_e32 vcc, v116, v117
	s_cbranch_vccz .LBB0_1022
	v_sub_f32_e32 v117, v117, v116
	v_exp_f32_e32 v136, v117
	s_nop 0
	v_mul_f32_e32 v50, v50, v136
	v_pk_mul_f32 v[32:33], v[32:33], v[136:137] op_sel_hi:[1,0]
	v_pk_mul_f32 v[30:31], v[30:31], v[136:137] op_sel_hi:[1,0]
	v_pk_mul_f32 v[28:29], v[28:29], v[136:137] op_sel_hi:[1,0]
	v_pk_mul_f32 v[26:27], v[26:27], v[136:137] op_sel_hi:[1,0]
	v_pk_mul_f32 v[24:25], v[24:25], v[136:137] op_sel_hi:[1,0]
	v_pk_mul_f32 v[22:23], v[22:23], v[136:137] op_sel_hi:[1,0]
	v_pk_mul_f32 v[20:21], v[20:21], v[136:137] op_sel_hi:[1,0]
	v_pk_mul_f32 v[18:19], v[18:19], v[136:137] op_sel_hi:[1,0]
	v_pk_mul_f32 v[16:17], v[16:17], v[136:137] op_sel_hi:[1,0]
	v_pk_mul_f32 v[14:15], v[14:15], v[136:137] op_sel_hi:[1,0]
	v_pk_mul_f32 v[12:13], v[12:13], v[136:137] op_sel_hi:[1,0]
	v_pk_mul_f32 v[10:11], v[10:11], v[136:137] op_sel_hi:[1,0]
	v_pk_mul_f32 v[8:9], v[8:9], v[136:137] op_sel_hi:[1,0]
	v_pk_mul_f32 v[6:7], v[6:7], v[136:137] op_sel_hi:[1,0]
	v_pk_mul_f32 v[4:5], v[4:5], v[136:137] op_sel_hi:[1,0]
	v_pk_mul_f32 v[2:3], v[2:3], v[136:137] op_sel_hi:[1,0]
.LBB0_1022:
	v_cvt_pk_bf16_f32 v138, v59, v60
	v_cvt_pk_bf16_f32 v139, v61, v54
	v_cvt_pk_bf16_f32 v140, v53, v56
	v_cvt_pk_bf16_f32 v141, v55, v58
	v_cvt_pk_bf16_f32 v54, v57, v62
	v_cvt_pk_bf16_f32 v55, v63, v64
	v_cvt_pk_bf16_f32 v56, v65, v118
	v_cvt_pk_bf16_f32 v57, v119, v120
	s_waitcnt vmcnt(7)
	ds_write_b128 v129, v[66:69]
	s_waitcnt vmcnt(6)
	ds_write_b128 v129, v[70:73] offset:1152
	s_waitcnt vmcnt(5)
	ds_write_b128 v129, v[98:101] offset:2304
	s_waitcnt vmcnt(4)
	ds_write_b128 v129, v[102:105] offset:3456
	ds_read_b64_tr_b16 v[58:59], v134
	ds_read_b64_tr_b16 v[60:61], v134 offset:1152
	s_waitcnt lgkmcnt(0)
	v_mfma_f32_32x32x16_bf16 v[18:33], v[58:61], v[138:141], v[18:33]
	v_mad_i64_i32 v[62:63], s[48:49], v115, s44, 0
	v_lshl_add_u64 v[102:103], v[124:125], 0, v[62:63]
	ds_read_b64_tr_b16 v[62:63], v134 offset:2304
	ds_read_b64_tr_b16 v[64:65], v134 offset:3456
	ds_read_b64_tr_b16 v[100:101], v134 offset:1216
	ds_read_b64_tr_b16 v[98:99], v134 offset:64
	v_add_co_u32_e32 v58, vcc, s46, v102
	v_add_f32_e32 v51, v51, v52
	s_nop 0
	v_addc_co_u32_e32 v59, vcc, 0, v103, vcc
	s_waitcnt lgkmcnt(2)
	v_mfma_f32_32x32x16_bf16 v[18:33], v[62:65], v[54:57], v[18:33]
	v_add_co_u32_e32 v62, vcc, s77, v102
	global_load_dwordx4 v[66:69], v[102:103], off
	global_load_dwordx4 v[70:73], v[58:59], off
	v_addc_co_u32_e32 v63, vcc, 0, v103, vcc
	v_add_co_u32_e32 v64, vcc, s45, v102
	ds_read_b64_tr_b16 v[60:61], v134 offset:3520
	ds_read_b64_tr_b16 v[58:59], v134 offset:2368
	v_addc_co_u32_e32 v65, vcc, 0, v103, vcc
	s_waitcnt lgkmcnt(2)
	v_mfma_f32_32x32x16_bf16 v[2:17], v[98:101], v[138:141], v[2:17]
	global_load_dwordx4 v[98:101], v[62:63], off
	global_load_dwordx4 v[102:105], v[64:65], off
	v_add_f32_e32 v136, v51, v50
	s_cmp_ge_i32 s43, s5
	s_waitcnt lgkmcnt(0)
	v_mfma_f32_32x32x16_bf16 v[2:17], v[58:61], v[54:57], v[2:17]
	s_cbranch_scc1 .LBB0_884
	s_waitcnt vmcnt(7)
	ds_write_b128 v129, v[74:77] offset:4608
	s_waitcnt vmcnt(6)
	ds_write_b128 v129, v[78:81] offset:5760
	s_waitcnt vmcnt(5)
	ds_write_b128 v129, v[106:109] offset:6912
	s_waitcnt vmcnt(4)
	ds_write_b128 v129, v[110:113] offset:8064
	ds_read_b128 v[50:53], v130 offset:4608
	ds_read_b128 v[74:77], v130 offset:4624
	ds_read_b128 v[78:81], v130 offset:4640
	ds_read_b128 v[106:109], v130 offset:4656
	s_waitcnt lgkmcnt(3)
	v_mfma_f32_32x32x16_bf16 v[50:65], v[50:53], v[82:85], 0
	s_add_i32 s2, s4, -1
	s_min_i32 s33, s2, s66
	s_add_i32 s33, s33, s78
	v_lshl_add_u32 v138, s33, 6, v131
	v_mad_i64_i32 v[110:111], s[48:49], v138, s44, v[126:127]
	s_waitcnt lgkmcnt(2)
	v_mfma_f32_32x32x16_bf16 v[50:65], v[74:77], v[86:89], v[50:65]
	global_load_dwordx4 v[74:77], v[110:111], off
	v_add_u32_e32 v115, -3, v137
	v_mov_b32_e32 v117, 0xff800000
	s_waitcnt lgkmcnt(1)
	v_mfma_f32_32x32x16_bf16 v[50:65], v[78:81], v[90:93], v[50:65]
	v_add_co_u32_e32 v78, vcc, 0xc000, v110
	s_nop 1
	v_addc_co_u32_e32 v79, vcc, 0, v111, vcc
	global_load_dwordx4 v[78:81], v[78:79], off
	s_waitcnt lgkmcnt(0)
	v_mfma_f32_32x32x16_bf16 v[50:65], v[106:109], v[94:97], v[50:65]
	v_add_co_u32_e32 v106, vcc, 0x18000, v110
	s_nop 1
	v_addc_co_u32_e32 v107, vcc, 0, v111, vcc
	v_add_co_u32_e32 v110, vcc, 0x24000, v110
	global_load_dwordx4 v[106:109], v[106:107], off
	s_nop 0
	v_addc_co_u32_e32 v111, vcc, 0, v111, vcc
	global_load_dwordx4 v[110:113], v[110:111], off
	v_cmp_gt_u32_e32 vcc, 8, v115
	ds_read_b32 v200, v135 offset:10896
	ds_read_b32 v201, v135 offset:10900
	ds_read_b32 v202, v135 offset:10904
	ds_read_b32 v203, v135 offset:10908
	ds_read_b32 v204, v135 offset:10928
	ds_read_b32 v205, v135 offset:10932
	ds_read_b32 v206, v135 offset:10936
	ds_read_b32 v207, v135 offset:10940
	ds_read_b32 v208, v135 offset:10960
	ds_read_b32 v209, v135 offset:10964
	ds_read_b32 v210, v135 offset:10968
	ds_read_b32 v211, v135 offset:10972
	ds_read_b32 v212, v135 offset:10992
	ds_read_b32 v213, v135 offset:10996
	ds_read_b32 v214, v135 offset:11000
	ds_read_b32 v215, v135 offset:11004
	s_waitcnt lgkmcnt(12)
	s_and_b64 s[48:49], vcc, s[6:7]
	v_add_f32_e32 v200, v34, v200
	v_cndmask_b32_e64 v117, v252, v200, s[48:49]
	s_and_b64 s[48:49], vcc, s[8:9]
	v_add_f32_e32 v201, v35, v201
	v_cndmask_b32_e64 v115, v252, v201, s[48:49]
	s_and_b64 s[48:49], vcc, s[10:11]
	v_add_f32_e32 v202, v36, v202
	v_cndmask_b32_e64 v35, v252, v202, s[48:49]
	s_and_b64 s[48:49], vcc, s[12:13]
	v_add_f32_e32 v203, v37, v203
	v_cndmask_b32_e64 v34, v252, v203, s[48:49]
	s_waitcnt lgkmcnt(8)
	s_and_b64 s[48:49], vcc, s[14:15]
	v_add_f32_e32 v204, v38, v204
	v_cndmask_b32_e64 v37, v252, v204, s[48:49]
	s_and_b64 s[48:49], vcc, s[16:17]
	v_add_f32_e32 v205, v39, v205
	v_cndmask_b32_e64 v36, v252, v205, s[48:49]
	s_and_b64 s[48:49], vcc, s[18:19]
	v_add_f32_e32 v206, v40, v206
	v_cndmask_b32_e64 v39, v252, v206, s[48:49]
	s_and_b64 s[48:49], vcc, s[20:21]
	v_add_f32_e32 v207, v41, v207
	v_cndmask_b32_e64 v38, v252, v207, s[48:49]
	s_waitcnt lgkmcnt(4)
	s_and_b64 s[48:49], vcc, s[22:23]
	v_add_f32_e32 v208, v42, v208
	v_cndmask_b32_e64 v119, v252, v208, s[48:49]
	s_and_b64 s[48:49], vcc, s[24:25]
	v_add_f32_e32 v209, v43, v209
	v_cndmask_b32_e64 v118, v252, v209, s[48:49]
	s_and_b64 s[48:49], vcc, s[26:27]
	v_add_f32_e32 v210, v44, v210
	v_cndmask_b32_e64 v121, v252, v210, s[48:49]
	s_and_b64 s[48:49], vcc, s[28:29]
	v_add_f32_e32 v211, v45, v211
	v_cndmask_b32_e64 v120, v252, v211, s[48:49]
	s_waitcnt lgkmcnt(0)
	s_and_b64 s[48:49], vcc, s[30:31]
	v_add_f32_e32 v212, v46, v212
	v_cndmask_b32_e64 v140, v252, v212, s[48:49]
	s_and_b64 s[48:49], vcc, s[34:35]
	v_add_f32_e32 v213, v47, v213
	v_cndmask_b32_e64 v123, v252, v213, s[48:49]
	s_and_b64 s[48:49], vcc, s[36:37]
	v_add_f32_e32 v214, v48, v214
	v_cndmask_b32_e64 v142, v252, v214, s[48:49]
	s_and_b64 s[48:49], vcc, s[38:39]
	v_add_f32_e32 v215, v49, v215
	v_cndmask_b32_e64 v141, v252, v215, s[48:49]
	v_max_f32_e32 v40, v115, v115
	v_max_f32_e32 v41, v117, v117
	v_max_f32_e32 v40, v41, v40
	v_max3_f32 v40, v40, v35, v34
	v_max3_f32 v40, v40, v37, v36
	v_max3_f32 v40, v40, v39, v38
	v_max3_f32 v40, v40, v119, v118
	v_max3_f32 v40, v40, v121, v120
	v_max3_f32 v40, v40, v140, v123
	v_max3_f32 v40, v40, v142, v141
	v_mov_b32_e32 v41, v40
	s_nop 1
	v_permlane32_swap_b32_e32 v40, v41
	v_max3_f32 v139, v116, v40, v41
	v_sub_f32_e32 v40, v117, v139
	v_exp_f32_e32 v40, v40
	v_sub_f32_e32 v41, v115, v139
	v_exp_f32_e32 v41, v41
	v_sub_f32_e32 v35, v35, v139
	v_exp_f32_e32 v35, v35
	v_sub_f32_e32 v34, v34, v139
	v_exp_f32_e32 v34, v34
	v_sub_f32_e32 v37, v37, v139
	v_add_f32_e32 v42, 0, v40
	v_exp_f32_e32 v37, v37
	v_sub_f32_e32 v36, v36, v139
	v_add_f32_e32 v42, v41, v42
	v_exp_f32_e32 v36, v36
	v_sub_f32_e32 v39, v39, v139
	v_add_f32_e32 v42, v35, v42
	v_exp_f32_e32 v39, v39
	v_sub_f32_e32 v38, v38, v139
	v_add_f32_e32 v42, v34, v42
	v_exp_f32_e32 v38, v38
	v_add_f32_e32 v42, v37, v42
	v_add_f32_e32 v42, v36, v42
	v_add_f32_e32 v42, v39, v42
	v_add_f32_e32 v46, v38, v42
	v_sub_f32_e32 v42, v119, v139
	v_exp_f32_e32 v42, v42
	v_sub_f32_e32 v43, v118, v139
	v_exp_f32_e32 v43, v43
	v_sub_f32_e32 v44, v121, v139
	v_exp_f32_e32 v44, v44
	v_sub_f32_e32 v45, v120, v139
	v_exp_f32_e32 v45, v45
	v_add_f32_e32 v46, v42, v46
	v_add_f32_e32 v46, v43, v46
	v_add_f32_e32 v46, v44, v46
	v_add_f32_e32 v115, v45, v46
	v_sub_f32_e32 v46, v140, v139
	v_exp_f32_e32 v46, v46
	v_sub_f32_e32 v47, v123, v139
	v_exp_f32_e32 v47, v47
	v_sub_f32_e32 v48, v142, v139
	v_exp_f32_e32 v48, v48
	v_sub_f32_e32 v49, v141, v139
	v_exp_f32_e32 v49, v49
	v_add_f32_e32 v115, v46, v115
	v_add_f32_e32 v115, v47, v115
	v_add_f32_e32 v115, v48, v115
	v_add_f32_e32 v123, v49, v115
	v_mov_b32_e32 v140, v123
	s_nop 1
	v_permlane32_swap_b32_e32 v123, v140
	v_cmp_gt_f32_e32 vcc, v139, v116
	s_cbranch_vccz .LBB0_1057
	v_sub_f32_e32 v115, v116, v139
	v_exp_f32_e32 v116, v115
	s_nop 0
	v_mul_f32_e32 v136, v136, v116
	v_pk_mul_f32 v[32:33], v[32:33], v[116:117] op_sel_hi:[1,0]
	v_pk_mul_f32 v[30:31], v[30:31], v[116:117] op_sel_hi:[1,0]
	v_pk_mul_f32 v[28:29], v[28:29], v[116:117] op_sel_hi:[1,0]
	v_pk_mul_f32 v[26:27], v[26:27], v[116:117] op_sel_hi:[1,0]
	v_pk_mul_f32 v[24:25], v[24:25], v[116:117] op_sel_hi:[1,0]
	v_pk_mul_f32 v[22:23], v[22:23], v[116:117] op_sel_hi:[1,0]
	v_pk_mul_f32 v[20:21], v[20:21], v[116:117] op_sel_hi:[1,0]
	v_pk_mul_f32 v[18:19], v[18:19], v[116:117] op_sel_hi:[1,0]
	v_pk_mul_f32 v[16:17], v[16:17], v[116:117] op_sel_hi:[1,0]
	v_pk_mul_f32 v[14:15], v[14:15], v[116:117] op_sel_hi:[1,0]
	v_pk_mul_f32 v[12:13], v[12:13], v[116:117] op_sel_hi:[1,0]
	v_pk_mul_f32 v[10:11], v[10:11], v[116:117] op_sel_hi:[1,0]
	v_pk_mul_f32 v[8:9], v[8:9], v[116:117] op_sel_hi:[1,0]
	v_pk_mul_f32 v[6:7], v[6:7], v[116:117] op_sel_hi:[1,0]
	v_pk_mul_f32 v[4:5], v[4:5], v[116:117] op_sel_hi:[1,0]
	v_pk_mul_f32 v[2:3], v[2:3], v[116:117] op_sel_hi:[1,0]
.LBB0_1057:
	v_cvt_pk_bf16_f32 v116, v40, v41
	v_cvt_pk_bf16_f32 v117, v35, v34
	v_cvt_pk_bf16_f32 v118, v37, v36
	v_cvt_pk_bf16_f32 v119, v39, v38
	v_cvt_pk_bf16_f32 v34, v42, v43
	v_cvt_pk_bf16_f32 v35, v44, v45
	v_cvt_pk_bf16_f32 v36, v46, v47
	v_cvt_pk_bf16_f32 v37, v48, v49
	s_waitcnt vmcnt(7)
	ds_write_b128 v129, v[66:69]
	s_waitcnt vmcnt(6)
	ds_write_b128 v129, v[70:73] offset:1152
	s_waitcnt vmcnt(5)
	ds_write_b128 v129, v[98:101] offset:2304
	s_waitcnt vmcnt(4)
	ds_write_b128 v129, v[102:105] offset:3456
	ds_read_b64_tr_b16 v[38:39], v134
	ds_read_b64_tr_b16 v[40:41], v134 offset:1152
	ds_read_b64_tr_b16 v[44:45], v134 offset:1216
	ds_read_b64_tr_b16 v[42:43], v134 offset:64
	s_waitcnt lgkmcnt(2)
	v_mfma_f32_32x32x16_bf16 v[18:33], v[38:41], v[116:119], v[18:33]
	ds_read_b64_tr_b16 v[38:39], v134 offset:2304
	ds_read_b64_tr_b16 v[40:41], v134 offset:3456
	v_mad_i64_i32 v[46:47], s[48:49], v114, s44, 0
	v_lshl_add_u64 v[98:99], v[124:125], 0, v[46:47]
	ds_read_b64_tr_b16 v[48:49], v134 offset:3520
	ds_read_b64_tr_b16 v[46:47], v134 offset:2368
	s_min_i32 s33, s4, s66
	s_add_i32 s33, s33, s78
	s_waitcnt lgkmcnt(2)
	v_mfma_f32_32x32x16_bf16 v[18:33], v[38:41], v[34:37], v[18:33]
	v_add_co_u32_e32 v38, vcc, s46, v98
	s_cmp_lt_i32 s42, s5
	s_nop 0
	v_addc_co_u32_e32 v39, vcc, 0, v99, vcc
	global_load_dwordx4 v[66:69], v[98:99], off
	global_load_dwordx4 v[70:73], v[38:39], off
	v_add_co_u32_e32 v38, vcc, s77, v98
	v_mfma_f32_32x32x16_bf16 v[2:17], v[42:45], v[116:119], v[2:17]
	s_nop 0
	v_addc_co_u32_e32 v39, vcc, 0, v99, vcc
	v_add_co_u32_e32 v40, vcc, s45, v98
	s_nop 1
	v_addc_co_u32_e32 v41, vcc, 0, v99, vcc
	global_load_dwordx4 v[114:117], v[38:39], off
	global_load_dwordx4 v[118:121], v[40:41], off
	s_waitcnt vmcnt(7)
	ds_write_b128 v129, v[74:77] offset:4608
	s_waitcnt vmcnt(6)
	ds_write_b128 v129, v[78:81] offset:5760
	s_waitcnt vmcnt(5)
	ds_write_b128 v129, v[106:109] offset:6912
	s_waitcnt vmcnt(4)
	ds_write_b128 v129, v[110:113] offset:8064
	s_waitcnt lgkmcnt(4)
	v_mfma_f32_32x32x16_bf16 v[2:17], v[46:49], v[34:37], v[2:17]
	ds_read_b128 v[34:37], v130 offset:4608
	ds_read_b128 v[74:77], v130 offset:4624
	s_waitcnt lgkmcnt(1)
	v_mfma_f32_32x32x16_bf16 v[34:49], v[34:37], v[82:85], 0
	s_waitcnt lgkmcnt(0)
	v_mfma_f32_32x32x16_bf16 v[34:49], v[74:77], v[86:89], v[34:49]
	ds_read_b128 v[74:77], v130 offset:4640
	ds_read_b128 v[78:81], v130 offset:4656
	s_waitcnt lgkmcnt(1)
	v_mfma_f32_32x32x16_bf16 v[34:49], v[74:77], v[90:93], v[34:49]
	v_lshl_add_u32 v74, s33, 6, v131
	v_mad_i64_i32 v[74:75], s[48:49], v74, s44, v[126:127]
	v_add_co_u32_e32 v76, vcc, s46, v74
	s_nop 1
	v_addc_co_u32_e32 v77, vcc, 0, v75, vcc
	global_load_dwordx4 v[102:105], v[74:75], off
	global_load_dwordx4 v[98:101], v[76:77], off
	v_add_co_u32_e32 v76, vcc, s77, v74
	s_waitcnt lgkmcnt(0)
	v_mfma_f32_32x32x16_bf16 v[34:49], v[78:81], v[94:97], v[34:49]
	v_addc_co_u32_e32 v77, vcc, 0, v75, vcc
	v_add_co_u32_e32 v74, vcc, s45, v74
	s_nop 1
	v_addc_co_u32_e32 v75, vcc, 0, v75, vcc
	global_load_dwordx4 v[106:109], v[76:77], off
	global_load_dwordx4 v[110:113], v[74:75], off
	v_mov_b32_e32 v74, 0xff800000
	s_cselect_b64 vcc, -1, 0
	v_cndmask_b32_e32 v75, v74, v58, vcc
	v_cndmask_b32_e32 v58, v74, v55, vcc
	v_cndmask_b32_e32 v55, v74, v54, vcc
	v_cndmask_b32_e32 v54, v74, v51, vcc
	v_add_u32_e32 v51, -2, v137
	v_cndmask_b32_e32 v65, v74, v65, vcc
	v_cndmask_b32_e32 v64, v74, v64, vcc
	v_cndmask_b32_e32 v63, v74, v63, vcc
	v_cndmask_b32_e32 v62, v74, v62, vcc
	v_cndmask_b32_e32 v61, v74, v61, vcc
	v_cndmask_b32_e32 v60, v74, v60, vcc
	v_cndmask_b32_e32 v59, v74, v59, vcc
	v_cndmask_b32_e32 v76, v74, v57, vcc
	v_cndmask_b32_e32 v57, v74, v56, vcc
	v_cndmask_b32_e32 v56, v74, v53, vcc
	v_cndmask_b32_e32 v53, v74, v52, vcc
	v_cndmask_b32_e32 v50, v74, v50, vcc
	v_cmp_gt_u32_e32 vcc, 8, v51
	ds_read_b32 v200, v135 offset:11020
	ds_read_b32 v201, v135 offset:11024
	ds_read_b32 v202, v135 offset:11028
	ds_read_b32 v203, v135 offset:11032
	ds_read_b32 v204, v135 offset:11052
	ds_read_b32 v205, v135 offset:11056
	ds_read_b32 v206, v135 offset:11060
	ds_read_b32 v207, v135 offset:11064
	ds_read_b32 v208, v135 offset:11084
	ds_read_b32 v209, v135 offset:11088
	ds_read_b32 v210, v135 offset:11092
	ds_read_b32 v211, v135 offset:11096
	ds_read_b32 v212, v135 offset:11116
	ds_read_b32 v213, v135 offset:11120
	ds_read_b32 v214, v135 offset:11124
	ds_read_b32 v215, v135 offset:11128
	s_waitcnt lgkmcnt(12)
	s_and_b64 s[42:43], vcc, s[6:7]
	v_add_f32_e32 v200, v50, v200
	v_cndmask_b32_e64 v51, v252, v200, s[42:43]
	s_and_b64 s[42:43], vcc, s[8:9]
	v_add_f32_e32 v201, v54, v201
	v_cndmask_b32_e64 v52, v252, v201, s[42:43]
	s_and_b64 s[42:43], vcc, s[10:11]
	v_add_f32_e32 v202, v53, v202
	v_cndmask_b32_e64 v74, v252, v202, s[42:43]
	s_and_b64 s[42:43], vcc, s[12:13]
	v_add_f32_e32 v203, v56, v203
	v_cndmask_b32_e64 v54, v252, v203, s[42:43]
	s_waitcnt lgkmcnt(8)
	s_and_b64 s[42:43], vcc, s[14:15]
	v_add_f32_e32 v204, v55, v204
	v_cndmask_b32_e64 v53, v252, v204, s[42:43]
	s_and_b64 s[42:43], vcc, s[16:17]
	v_add_f32_e32 v205, v58, v205
	v_cndmask_b32_e64 v56, v252, v205, s[42:43]
	s_and_b64 s[42:43], vcc, s[18:19]
	v_add_f32_e32 v206, v57, v206
	v_cndmask_b32_e64 v55, v252, v206, s[42:43]
	s_and_b64 s[42:43], vcc, s[20:21]
	v_add_f32_e32 v207, v76, v207
	v_cndmask_b32_e64 v58, v252, v207, s[42:43]
	s_waitcnt lgkmcnt(4)
	s_and_b64 s[42:43], vcc, s[22:23]
	v_add_f32_e32 v208, v75, v208
	v_cndmask_b32_e64 v57, v252, v208, s[42:43]
	s_and_b64 s[42:43], vcc, s[24:25]
	v_add_f32_e32 v209, v59, v209
	v_cndmask_b32_e64 v76, v252, v209, s[42:43]
	s_and_b64 s[42:43], vcc, s[26:27]
	v_add_f32_e32 v210, v60, v210
	v_cndmask_b32_e64 v75, v252, v210, s[42:43]
	s_and_b64 s[42:43], vcc, s[28:29]
	v_add_f32_e32 v211, v61, v211
	v_cndmask_b32_e64 v78, v252, v211, s[42:43]
	s_waitcnt lgkmcnt(0)
	s_and_b64 s[42:43], vcc, s[30:31]
	v_add_f32_e32 v212, v62, v212
	v_cndmask_b32_e64 v77, v252, v212, s[42:43]
	s_and_b64 s[42:43], vcc, s[34:35]
	v_add_f32_e32 v213, v63, v213
	v_cndmask_b32_e64 v80, v252, v213, s[42:43]
	s_and_b64 s[42:43], vcc, s[36:37]
	v_add_f32_e32 v214, v64, v214
	v_cndmask_b32_e64 v79, v252, v214, s[42:43]
	s_and_b64 s[42:43], vcc, s[38:39]
	v_add_f32_e32 v215, v65, v215
	v_cndmask_b32_e64 v81, v252, v215, s[42:43]
	v_max_f32_e32 v59, v52, v52
	v_max_f32_e32 v60, v51, v51
	v_max_f32_e32 v59, v60, v59
	v_max3_f32 v59, v59, v74, v54
	v_max3_f32 v59, v59, v53, v56
	v_max3_f32 v59, v59, v55, v58
	v_max3_f32 v59, v59, v57, v76
	v_max3_f32 v59, v59, v75, v78
	v_max3_f32 v59, v59, v77, v80
	v_max3_f32 v59, v59, v79, v81
	v_mov_b32_e32 v60, v59
	s_nop 1
	v_permlane32_swap_b32_e32 v59, v60
	v_add_f32_e32 v50, v123, v140
	v_max3_f32 v123, v139, v59, v60
	v_sub_f32_e32 v51, v51, v123
	v_exp_f32_e32 v59, v51
	v_sub_f32_e32 v51, v52, v123
	v_exp_f32_e32 v60, v51
	v_sub_f32_e32 v51, v74, v123
	v_exp_f32_e32 v61, v51
	v_sub_f32_e32 v51, v54, v123
	v_exp_f32_e32 v54, v51
	v_sub_f32_e32 v52, v53, v123
	v_add_f32_e32 v51, 0, v59
	v_exp_f32_e32 v53, v52
	v_sub_f32_e32 v52, v56, v123
	v_add_f32_e32 v51, v60, v51
	v_exp_f32_e32 v56, v52
	v_sub_f32_e32 v52, v55, v123
	v_add_f32_e32 v51, v61, v51
	v_exp_f32_e32 v55, v52
	v_sub_f32_e32 v52, v58, v123
	v_add_f32_e32 v51, v54, v51
	v_exp_f32_e32 v58, v52
	v_sub_f32_e32 v52, v57, v123
	v_add_f32_e32 v51, v53, v51
	v_exp_f32_e32 v57, v52
	v_sub_f32_e32 v52, v76, v123
	v_add_f32_e32 v51, v56, v51
	v_exp_f32_e32 v62, v52
	v_sub_f32_e32 v52, v75, v123
	v_add_f32_e32 v51, v55, v51
	v_exp_f32_e32 v63, v52
	v_sub_f32_e32 v52, v78, v123
	v_add_f32_e32 v51, v58, v51
	v_exp_f32_e32 v64, v52
	v_sub_f32_e32 v52, v77, v123
	v_add_f32_e32 v51, v57, v51
	v_exp_f32_e32 v65, v52
	v_sub_f32_e32 v52, v80, v123
	v_add_f32_e32 v51, v62, v51
	v_exp_f32_e32 v74, v52
	v_sub_f32_e32 v52, v79, v123
	v_add_f32_e32 v51, v63, v51
	v_exp_f32_e32 v75, v52
	v_sub_f32_e32 v52, v81, v123
	v_add_f32_e32 v51, v64, v51
	v_exp_f32_e32 v76, v52
	v_add_f32_e32 v51, v65, v51
	v_add_f32_e32 v51, v74, v51
	v_add_f32_e32 v51, v75, v51
	v_add_f32_e32 v51, v76, v51
	v_mov_b32_e32 v52, v51
	v_add_f32_e32 v50, v50, v136
	s_nop 0
	v_permlane32_swap_b32_e32 v51, v52
	v_cmp_gt_f32_e32 vcc, v123, v139
	s_cbranch_vccz .LBB0_1091
	v_sub_f32_e32 v77, v139, v123
	v_exp_f32_e32 v78, v77
	s_nop 0
	v_mul_f32_e32 v50, v50, v78
	v_pk_mul_f32 v[32:33], v[32:33], v[78:79] op_sel_hi:[1,0]
	v_pk_mul_f32 v[30:31], v[30:31], v[78:79] op_sel_hi:[1,0]
	v_pk_mul_f32 v[28:29], v[28:29], v[78:79] op_sel_hi:[1,0]
	v_pk_mul_f32 v[26:27], v[26:27], v[78:79] op_sel_hi:[1,0]
	v_pk_mul_f32 v[24:25], v[24:25], v[78:79] op_sel_hi:[1,0]
	v_pk_mul_f32 v[22:23], v[22:23], v[78:79] op_sel_hi:[1,0]
	v_pk_mul_f32 v[20:21], v[20:21], v[78:79] op_sel_hi:[1,0]
	v_pk_mul_f32 v[18:19], v[18:19], v[78:79] op_sel_hi:[1,0]
	v_pk_mul_f32 v[16:17], v[16:17], v[78:79] op_sel_hi:[1,0]
	v_pk_mul_f32 v[14:15], v[14:15], v[78:79] op_sel_hi:[1,0]
	v_pk_mul_f32 v[12:13], v[12:13], v[78:79] op_sel_hi:[1,0]
	v_pk_mul_f32 v[10:11], v[10:11], v[78:79] op_sel_hi:[1,0]
	v_pk_mul_f32 v[8:9], v[8:9], v[78:79] op_sel_hi:[1,0]
	v_pk_mul_f32 v[6:7], v[6:7], v[78:79] op_sel_hi:[1,0]
	v_pk_mul_f32 v[4:5], v[4:5], v[78:79] op_sel_hi:[1,0]
	v_pk_mul_f32 v[2:3], v[2:3], v[78:79] op_sel_hi:[1,0]
